# idx units: next unit's query-fragment lines touched (one dword per line) during the selection of the current unit
# speedup vs baseline: 1.0071x; 1.0032x over previous
; __device__ __forceinline__ void idx_unit(unsigned char* lds, const bf16_t* P, int b, int qb16, unsigned* bits) {
;     ...
;     for (int rb = 0; rb < 4; ++rb) { const bf16_t* ap = P + (tok0 + rb * 4 + (r32 >> 3)) * PW + P_IQ + (r32 & 7) * 64 + 8 * hi;
; #pragma unroll
;         for (int kk = 0; kk < 4; ++kk) aq[rb][kk] = *(const bf16x8*)(ap + kk * 16); }
; __global__ void __launch_bounds__(512, 2) fwd_kernel(Args a) {
;     ...
;         for (int it = cb_; it < 4096; it += G) idx_unit(lds, P, it & 15, it >> 4, BITS);
.LBB0_412:
	s_or_b64 exec, exec, s[0:1]
	s_waitcnt vmcnt(0)
	s_add_i32 s0, s76, s34
	s_cmpk_gt_i32 s0, 0xfff
	s_cbranch_scc1 .Lpf_idx_skip
	s_and_b32 s1, s0, -16
	s_bitcmp1_b32 s0, 8
	s_cselect_b32 s100, 0xf0, 0
	s_xor_b32 s1, s1, s100
	s_add_i32 s1, s1, s64
	v_lshrrev_b32_e32 v218, 3, v182
	v_add_u32_e32 v218, s1, v218
	v_mul_lo_u32 v218, s37, v218
	v_mov_b32_e32 v219, 0
	v_lshl_add_u64 v[218:219], v[218:219], 0, s[46:47]
	v_and_b32_e32 v220, 7, v182
	v_lshlrev_b32_e32 v220, 7, v220
	v_add_u32_e32 v220, 0x1000, v220
	v_mov_b32_e32 v221, 0
	v_lshl_add_u64 v[218:219], v[218:219], 0, v[220:221]
	v_cmp_gt_i32_e32 vcc, 0x80, v182
	s_and_saveexec_b64 s[0:1], vcc
	s_cbranch_execz .Lpf_idx_none
	global_load_dword v222, v[218:219], off

; template <int NCH>
; __device__ __forceinline__ void idx_select(const unsigned short* sc, unsigned* bits, size_t tok0, int tid) {
;     const int row = tid >> 5, j = tid & 31, lane = tid & 63;
;     unsigned kw[4 * NCH];
;     { const u32x4v* src = (const u32x4v*)(sc + row * 4096) + j;
; #pragma unroll
;       for (int i = 0; i < NCH; ++i) { const u32x4v v = src[i * 32]; kw[4 * i] = v.x; kw[4 * i + 1] = v.y; kw[4 * i + 2] = v.z; kw[4 * i + 3] = v.w; } }
;     const unsigned one2 = 0x00010001u;
;     unsigned lo = 1u, hi_ = 0xFFFFu;
; #pragma unroll 1
;     for (int it = 0; it < 16; ++it) { const unsigned mid = (lo + hi_ + 1u) >> 1, mid2 = mid | (mid << 16);
; __device__ __forceinline__ void idx_unit(unsigned char* lds, const bf16_t* P, int b, int qb16, unsigned* bits) {
;     ...
;     { const int z0 = ncomp * 32, zn = (nscan - z0) >> 3;
;       for (int e = tid; e < zn * 16; e += 512) { const int r = e / zn, c = e - r * zn; *(u32x4v*)(sc + r * 4096 + z0 + 8 * c) = (u32x4v){0u, 0u, 0u, 0u}; } }
;     __syncthreads();
;     switch (nscan >> 9) {
;         case 1: idx_select<2>(sc, bits, tok0, tid); break;
;         case 2: idx_select<4>(sc, bits, tok0, tid); break;
;         case 3: idx_select<6>(sc, bits, tok0, tid); break;
;         case 4: idx_select<8>(sc, bits, tok0, tid); break;
;         case 5: idx_select<10>(sc, bits, tok0, tid); break;
;         case 6: idx_select<12>(sc, bits, tok0, tid); break;
;         case 7: idx_select<14>(sc, bits, tok0, tid); break;
;         default: idx_select<16>(sc, bits, tok0, tid); break;
;     }
.Lpf_idx_skip:
	v_ashrrev_i32_e32 v66, 5, v182
	v_lshlrev_b32_e32 v0, 13, v66
	v_lshlrev_b32_e32 v2, 4, v178
	v_add3_u32 v68, 0, v0, v2
	s_waitcnt lgkmcnt(0)
	s_barrier
	ds_read_b128 v[6:9], v68
	ds_read_b128 v[2:5], v68 offset:512
	s_ashr_i32 s64, s8, 9
	s_mov_b64 s[0:1], -1
	s_mov_b64 s[72:73], 0
	s_cmp_lt_i32 s64, 4
	s_mov_b64 s[74:75], 0
	s_cbranch_scc1 .LBB0_687
	s_cmp_gt_i32 s64, 5
	s_cbranch_scc0 .LBB0_575
	s_cmp_gt_i32 s64, 6
	s_cbranch_scc0 .LBB0_502
	s_cmp_eq_u32 s64, 7
	s_mov_b64 s[74:75], -1
	s_cbranch_scc0 .LBB0_501
	ds_read_b128 v[54:57], v68 offset:1024
	ds_read_b128 v[50:53], v68 offset:1536
	ds_read_b128 v[46:49], v68 offset:2048
	ds_read_b128 v[42:45], v68 offset:2560
	ds_read_b128 v[38:41], v68 offset:3072
	ds_read_b128 v[34:37], v68 offset:3584
	ds_read_b128 v[30:33], v68 offset:4096
	ds_read_b128 v[26:29], v68 offset:4608
	ds_read_b128 v[22:25], v68 offset:5120
	ds_read_b128 v[18:21], v68 offset:5632
	ds_read_b128 v[14:17], v68 offset:6144
	ds_read_b128 v[10:13], v68 offset:6656
	v_mov_b32_e32 v59, 0xffff
	v_mov_b32_e32 v0, 1
	v_mov_b32_e32 v58, 15
